# NSA block selection rewritten: lane=(query,32-block range), bisection counts via v_cmp+addc and DPP reduce instead of 8 serial per-query ballot loops; plus v4 SwiGLU epilogue
# speedup vs baseline: 1.0160x; 1.0160x over previous
; #define LAS __attribute__((address_space(3)))
; DI void cmpwin_unit(const Params& P, lptr L, int u, int tid, int lane, int wid) {
;     ...
;             const LAS float* tp_ = (const LAS float*)(L + AL_TMP) + ((NTC - 1) & 1) * (8 * 17 * 32);
;             for (int e = tid; e < 2 * 17 * 32; e += 512) { const int q32 = e & 31, jl = (e >> 5) % 17, qh = e / (17 * 32);
;                 const float a = (tp_[((qh * 4 + 0) * 17 + jl) * 32 + q32] + tp_[((qh * 4 + 1) * 17 + jl) * 32 + q32]) + (tp_[((qh * 4 + 2) * 17 + jl) * 32 + q32] + tp_[((qh * 4 + 3) * 17 + jl) * 32 + q32]);
;                 psl[((NTC - 1) * 16 + jl) * PSL_P + qh * 32 + q32] += a; }
;             __syncthreads();
;         }
;         float* prow = PART + row * 512 + head * 64;
; #pragma unroll
;         for (int g4 = 0; g4 < 4; ++g4) {
;             *(f32x4*)(prow + 8 * g4 + 4 * hi) = (f32x4){o0[4 * g4] * gc, o0[4 * g4 + 1] * gc, o0[4 * g4 + 2] * gc, o0[4 * g4 + 3] * gc};
;             *(f32x4*)(prow + 32 + 8 * g4 + 4 * hi) = (f32x4){o1[4 * g4] * gc, o1[4 * g4 + 1] * gc, o1[4 * g4 + 2] * gc, o1[4 * g4 + 3] * gc};
;         }
;     ...
;         const int cur = qb;
;         const int nforced = cur == 0 ? 1 : (cur == 1 ? 2 : 3);
;         const int ncand = max(0, cur - 2), K = min(16, cur + 1) - nforced;
;         const unsigned long long lt_mask = (1ull << lane) - 1ull;
;         for (int qq = 0; qq < 8; ++qq) {
;             const int q = wid * 8 + qq; const int tq = qb * 64 + q;
;             unsigned key[4]; bool cand[4], selb[4];
; #pragma unroll
;             for (int ii = 0; ii < 4; ++ii) { const int j = lane + 64 * ii; key[ii] = __float_as_uint(psl[j * PSL_P + q]);
;                 cand[ii] = (j >= 1) && (j <= cur - 2); selb[ii] = (j == 0) || (j == cur) || (j == cur - 1); }
;             if (K >= ncand) {
; #pragma unroll
;                 for (int ii = 0; ii < 4; ++ii) selb[ii] = selb[ii] || cand[ii];
.LBB0_559:
	v_subrev_u32_e32 v37, 17, v35
	v_cmp_gt_u32_e32 vcc, s11, v36
	s_nop 1
	v_cndmask_b32_e32 v37, v37, v35, vcc
	v_cmp_lt_u32_e32 vcc, s76, v36
	v_add_u32_e32 v35, 16, v35
	s_nop 0
	v_cndmask_b32_e32 v38, 0, v212, vcc
	v_add_u32_e32 v38, v37, v38
	v_lshl_add_u32 v39, v38, 7, v34
	ds_read_b32 v38, v39
	ds_read_b32 v40, v39 offset:2176
	ds_read_b32 v41, v39 offset:4352
	ds_read_b32 v39, v39 offset:6528
	v_add_u32_e32 v37, s2, v37
	v_mul_lo_u32 v37, v37, s6
	v_add_u32_e32 v37, 0, v37
	s_waitcnt lgkmcnt(0)
	v_pk_add_f32 v[38:39], v[40:41], v[38:39]
	s_nop 0
	v_add_f32_e32 v38, v38, v39
	v_cndmask_b32_e32 v39, 0, v213, vcc
	v_lshlrev_b32_e32 v40, 2, v122
	v_add3_u32 v37, v37, v39, v40
	ds_read_b32 v39, v37 offset:37888
	v_cmp_lt_u32_e32 vcc, s77, v36
	s_or_b64 s[0:1], vcc, s[0:1]
	s_waitcnt lgkmcnt(0)
	v_add_f32_e32 v38, v39, v38
	ds_write_b32 v37, v38 offset:37888
	v_add_u32_e32 v37, 0x200, v36
	v_mov_b32_e32 v36, v37
	s_andn2_b64 exec, exec, s[0:1]
	s_cbranch_execnz .LBB0_559
	s_or_b64 exec, exec, s[0:1]
	v_add_f32_e32 v34, 1.0, v84
	v_div_scale_f32 v35, s[0:1], v34, v34, 1.0
	v_rcp_f32_e32 v36, v35
	v_div_scale_f32 v37, vcc, 1.0, v34, 1.0
	s_lshl_b32 s60, s51, 2
	v_fma_f32 v38, -v35, v36, 1.0
	v_fmac_f32_e32 v36, v38, v36
	v_mul_f32_e32 v38, v37, v36
	v_fma_f32 v39, -v35, v38, v37
	v_readlane_b32 s0, v250, 0
	v_fmac_f32_e32 v38, v39, v36
	v_readlane_b32 s1, v250, 1
	s_add_u32 s0, s0, s60
	v_fma_f32 v35, -v35, v38, v37
	s_addc_u32 s1, s1, 0
	v_div_fmas_f32 v35, v35, v36, v38
	v_lshlrev_b64 v[36:37], 11, v[0:1]
	s_cmpk_eq_i32 s61, 0xfe
	v_lshl_add_u64 v[36:37], s[0:1], 0, v[36:37]
	s_cselect_b32 s0, -2, -3
	s_cmpk_lg_i32 s61, 0xff
	s_cselect_b32 s33, s0, -1
	s_sub_i32 s1, 0x100, s61
	s_sub_i32 s2, 0xfd, s61
	s_min_u32 s1, s1, 16
	s_max_i32 s0, s2, 0
	s_add_i32 s33, s33, s1
	s_sub_i32 s3, 0xfe, s61
	v_div_fixup_f32 v34, v35, v34, 1.0
	v_lshlrev_b32_e32 v154, 2, v134
	v_mov_b32_e32 v155, v1
	s_cmp_lt_i32 s33, s0
	v_readlane_b32 s0, v250, 23
	v_lshl_add_u64 v[158:159], v[36:37], 0, v[154:155]
	v_pk_mul_f32 v[2:3], v[34:35], v[2:3] op_sel_hi:[0,1]
	v_pk_mul_f32 v[4:5], v[34:35], v[4:5] op_sel_hi:[0,1]
	v_cmp_ge_i32_e32 vcc, s2, v192
	v_readlane_b32 s1, v250, 24
	s_waitcnt lgkmcnt(0)
	s_barrier
	global_store_dwordx4 v[158:159], v[2:5], off
	s_cselect_b64 s[28:29], -1, 0
	s_and_b64 s[70:71], s[0:1], vcc
	v_pk_mul_f32 v[2:3], v[34:35], v[18:19] op_sel_hi:[0,1]
	v_pk_mul_f32 v[4:5], v[34:35], v[20:21] op_sel_hi:[0,1]
	v_cmp_eq_u32_e32 vcc, s41, v192
	global_store_dwordx4 v[158:159], v[2:5], off offset:128
	s_or_b64 s[0:1], s[12:13], vcc
	v_cmp_eq_u32_e32 vcc, s3, v192
	v_pk_mul_f32 v[2:3], v[34:35], v[6:7] op_sel_hi:[0,1]
	v_pk_mul_f32 v[4:5], v[34:35], v[8:9] op_sel_hi:[0,1]
	global_store_dwordx4 v[158:159], v[2:5], off offset:32
	s_or_b64 s[78:79], s[0:1], vcc
	v_cmp_eq_u32_e32 vcc, s41, v175
	v_pk_mul_f32 v[2:3], v[34:35], v[22:23] op_sel_hi:[0,1]
	v_pk_mul_f32 v[4:5], v[34:35], v[24:25] op_sel_hi:[0,1]
	v_cmp_eq_u32_e64 s[0:1], s3, v175
	global_store_dwordx4 v[158:159], v[2:5], off offset:160
	s_or_b64 s[30:31], vcc, s[0:1]
	v_cmp_eq_u32_e32 vcc, s41, v176
	v_pk_mul_f32 v[2:3], v[34:35], v[10:11] op_sel_hi:[0,1]
	v_pk_mul_f32 v[4:5], v[34:35], v[12:13] op_sel_hi:[0,1]
	v_cmp_eq_u32_e64 s[0:1], s3, v176
	global_store_dwordx4 v[158:159], v[2:5], off offset:64
	s_or_b64 s[64:65], vcc, s[0:1]
	v_cmp_eq_u32_e32 vcc, s41, v178
	v_pk_mul_f32 v[2:3], v[34:35], v[26:27] op_sel_hi:[0,1]
	v_pk_mul_f32 v[4:5], v[34:35], v[28:29] op_sel_hi:[0,1]
	v_cmp_eq_u32_e64 s[0:1], s3, v178
	global_store_dwordx4 v[158:159], v[2:5], off offset:192
	v_cmp_ge_i32_e64 s[22:23], s2, v175
	v_cmp_ge_i32_e64 s[24:25], s2, v176
	v_pk_mul_f32 v[2:3], v[34:35], v[14:15] op_sel_hi:[0,1]
	v_pk_mul_f32 v[4:5], v[34:35], v[16:17] op_sel_hi:[0,1]
	v_cmp_ge_i32_e64 s[26:27], s2, v178
	s_or_b64 s[74:75], vcc, s[0:1]
	global_store_dwordx4 v[158:159], v[2:5], off offset:96
	s_mov_b32 s82, 0
	s_mov_b32 s39, s41
	v_pk_mul_f32 v[2:3], v[34:35], v[30:31] op_sel_hi:[0,1]
	v_pk_mul_f32 v[4:5], v[34:35], v[32:33] op_sel_hi:[0,1]
	s_or_b64 s[68:69], s[78:79], s[70:71]
	s_or_b64 s[2:3], s[30:31], s[22:23]
	s_or_b64 s[42:43], s[64:65], s[24:25]
	s_or_b64 s[58:59], s[74:75], s[26:27]
	global_store_dwordx4 v[158:159], v[2:5], off offset:224
	v_and_b32_e32 v12, 7, v192
	v_lshrrev_b32_e32 v13, 3, v192
	v_add_u32_e32 v13, s93, v13
	v_lshlrev_b32_e32 v14, 5, v12
	v_mul_u32_u24_e32 v15, 0x2080, v12
	v_lshl_add_u32 v15, v13, 2, v15
	ds_read_b32 v228, v15 offset:37888
	ds_read_b32 v229, v15 offset:38148
	ds_read_b32 v230, v15 offset:38408
	ds_read_b32 v231, v15 offset:38668
	ds_read_b32 v232, v15 offset:38928
	ds_read_b32 v233, v15 offset:39188
	ds_read_b32 v234, v15 offset:39448
	ds_read_b32 v235, v15 offset:39708
	ds_read_b32 v236, v15 offset:39968
	ds_read_b32 v237, v15 offset:40228
	ds_read_b32 v238, v15 offset:40488
	ds_read_b32 v239, v15 offset:40748
	ds_read_b32 v240, v15 offset:41008
	ds_read_b32 v241, v15 offset:41268
	ds_read_b32 v242, v15 offset:41528
	ds_read_b32 v243, v15 offset:41788
	ds_read_b32 v244, v15 offset:42048
	ds_read_b32 v245, v15 offset:42308
	ds_read_b32 v246, v15 offset:42568
	ds_read_b32 v247, v15 offset:42828
	ds_read_b32 v248, v15 offset:43088
	ds_read_b32 v249, v15 offset:43348
	ds_read_b32 v252, v15 offset:43608
	ds_read_b32 v253, v15 offset:43868
	ds_read_b32 v254, v15 offset:44128
	ds_read_b32 v255, v15 offset:44388
	ds_read_b32 v6, v15 offset:44648
	ds_read_b32 v7, v15 offset:44908
	ds_read_b32 v8, v15 offset:45168
	ds_read_b32 v9, v15 offset:45428
	ds_read_b32 v10, v15 offset:45688
	ds_read_b32 v11, v15 offset:45948
	s_add_i32 s100, s39, -1
	s_lshl_b32 s101, s93, 5
	s_add_i32 s101, s101, 0x19904
	v_mov_b32_e32 v18, 1
	v_mov_b32_e32 v19, 0
	v_sub_u32_e32 v16, s100, v14
	v_max_i32_e32 v16, 0, v16
	v_min_i32_e32 v16, 32, v16
	v_lshlrev_b64 v[20:21], v16, v[18:19]
	v_add_u32_e32 v22, -1, v20
	v_cmp_eq_u32_e32 vcc, 0, v12
	s_nop 1
	v_cndmask_b32_e64 v23, 0, 1, vcc
	v_xor_b32_e32 v24, -1, v23
	v_and_b32_e32 v22, v22, v24
	v_sub_u32_e32 v25, s39, v14
	v_cmp_gt_u32_e32 vcc, 32, v25
	v_lshlrev_b32_e64 v24, v25, 1
	s_nop 0
	v_cndmask_b32_e32 v24, 0, v24, vcc
	v_or_b32_e32 v23, v23, v24
	v_sub_u32_e32 v25, s100, v14
	v_cmp_gt_u32_e32 vcc, 32, v25
	v_lshlrev_b32_e64 v24, v25, 1
	s_nop 0
	v_cndmask_b32_e32 v24, 0, v24, vcc
	v_or_b32_e32 v23, v23, v24
	v_or_b32_e32 v32, v23, v22
	s_and_b64 vcc, exec, s[28:29]
	s_cbranch_vccz .Lsel_store
; DI void cmpwin_unit(const Params& P, lptr L, int u, int tid, int lane, int wid) {
;     ...
;             for (int ii = 0; ii < 4; ++ii) { const int j = lane + 64 * ii; key[ii] = __float_as_uint(psl[j * PSL_P + q]);
;                 cand[ii] = (j >= 1) && (j <= cur - 2); selb[ii] = (j == 0) || (j == cur) || (j == cur - 1); }
;             if (K >= ncand) {
; #pragma unroll
;                 for (int ii = 0; ii < 4; ++ii) selb[ii] = selb[ii] || cand[ii];
;             } else {
;                 unsigned tau = 0u;
;     ...
;                     const unsigned trial = tau | (1u << bit);
;                     int cnt = 0;
; #pragma unroll
;                     for (int ii = 0; ii < 4; ++ii) cnt += __popcll(__ballot(cand[ii] && key[ii] >= trial));
;                     if (cnt == K) { tau = trial - 1u; break; }
;                     if (cnt > K) tau = trial;
;                 }
	s_waitcnt lgkmcnt(0)
	v_bfe_i32 v24, v22, 0, 1
	v_and_b32_e32 v228, v228, v24
	v_bfe_i32 v25, v22, 1, 1
	v_and_b32_e32 v229, v229, v25
	v_bfe_i32 v24, v22, 2, 1
	v_and_b32_e32 v230, v230, v24
	v_bfe_i32 v25, v22, 3, 1
	v_and_b32_e32 v231, v231, v25
	v_bfe_i32 v24, v22, 4, 1
	v_and_b32_e32 v232, v232, v24
	v_bfe_i32 v25, v22, 5, 1
	v_and_b32_e32 v233, v233, v25
	v_bfe_i32 v24, v22, 6, 1
	v_and_b32_e32 v234, v234, v24
	v_bfe_i32 v25, v22, 7, 1
	v_and_b32_e32 v235, v235, v25
	v_bfe_i32 v24, v22, 8, 1
	v_and_b32_e32 v236, v236, v24
	v_bfe_i32 v25, v22, 9, 1
	v_and_b32_e32 v237, v237, v25
	v_bfe_i32 v24, v22, 10, 1
	v_and_b32_e32 v238, v238, v24
	v_bfe_i32 v25, v22, 11, 1
	v_and_b32_e32 v239, v239, v25
	v_bfe_i32 v24, v22, 12, 1
	v_and_b32_e32 v240, v240, v24
	v_bfe_i32 v25, v22, 13, 1
	v_and_b32_e32 v241, v241, v25
	v_bfe_i32 v24, v22, 14, 1
	v_and_b32_e32 v242, v242, v24
	v_bfe_i32 v25, v22, 15, 1
	v_and_b32_e32 v243, v243, v25
	v_bfe_i32 v24, v22, 16, 1
	v_and_b32_e32 v244, v244, v24
	v_bfe_i32 v25, v22, 17, 1
	v_and_b32_e32 v245, v245, v25
	v_bfe_i32 v24, v22, 18, 1
	v_and_b32_e32 v246, v246, v24
	v_bfe_i32 v25, v22, 19, 1
	v_and_b32_e32 v247, v247, v25
	v_bfe_i32 v24, v22, 20, 1
	v_and_b32_e32 v248, v248, v24
	v_bfe_i32 v25, v22, 21, 1
	v_and_b32_e32 v249, v249, v25
	v_bfe_i32 v24, v22, 22, 1
	v_and_b32_e32 v252, v252, v24
	v_bfe_i32 v25, v22, 23, 1
	v_and_b32_e32 v253, v253, v25
	v_bfe_i32 v24, v22, 24, 1
	v_and_b32_e32 v254, v254, v24
	v_bfe_i32 v25, v22, 25, 1
	v_and_b32_e32 v255, v255, v25
	v_bfe_i32 v24, v22, 26, 1
	v_and_b32_e32 v6, v6, v24
	v_bfe_i32 v25, v22, 27, 1
	v_and_b32_e32 v7, v7, v25
	v_bfe_i32 v24, v22, 28, 1
	v_and_b32_e32 v8, v8, v24
	v_bfe_i32 v25, v22, 29, 1
	v_and_b32_e32 v9, v9, v25
	v_bfe_i32 v24, v22, 30, 1
	v_and_b32_e32 v10, v10, v24
	v_bfe_i32 v25, v22, 31, 1
	v_and_b32_e32 v11, v11, v25
	v_mov_b32_e32 v26, 0
	s_mov_b64 s[52:53], 0
	s_mov_b32 s98, 30
.Lsel_loop:
	s_lshl_b32 s99, 1, s98
	v_or_b32_e32 v27, s99, v26
	v_mov_b32_e32 v28, 0
	v_mov_b32_e32 v29, 0
	v_cmp_ge_u32_e64 s[22:23], v228, v27
	v_cmp_ge_u32_e64 s[24:25], v229, v27
	v_cmp_ge_u32_e64 s[26:27], v230, v27
	v_addc_co_u32_e64 v28, vcc, v28, 0, s[22:23]
	v_cmp_ge_u32_e64 s[22:23], v231, v27
	v_addc_co_u32_e64 v29, vcc, v29, 0, s[24:25]
	v_cmp_ge_u32_e64 s[24:25], v232, v27
	v_addc_co_u32_e64 v28, vcc, v28, 0, s[26:27]
	v_cmp_ge_u32_e64 s[26:27], v233, v27
	v_addc_co_u32_e64 v29, vcc, v29, 0, s[22:23]
	v_cmp_ge_u32_e64 s[22:23], v234, v27
	v_addc_co_u32_e64 v28, vcc, v28, 0, s[24:25]
	v_cmp_ge_u32_e64 s[24:25], v235, v27
	v_addc_co_u32_e64 v29, vcc, v29, 0, s[26:27]
	v_cmp_ge_u32_e64 s[26:27], v236, v27
	v_addc_co_u32_e64 v28, vcc, v28, 0, s[22:23]
	v_cmp_ge_u32_e64 s[22:23], v237, v27
	v_addc_co_u32_e64 v29, vcc, v29, 0, s[24:25]
	v_cmp_ge_u32_e64 s[24:25], v238, v27
	v_addc_co_u32_e64 v28, vcc, v28, 0, s[26:27]
	v_cmp_ge_u32_e64 s[26:27], v239, v27
	v_addc_co_u32_e64 v29, vcc, v29, 0, s[22:23]
	v_cmp_ge_u32_e64 s[22:23], v240, v27
	v_addc_co_u32_e64 v28, vcc, v28, 0, s[24:25]
	v_cmp_ge_u32_e64 s[24:25], v241, v27
	v_addc_co_u32_e64 v29, vcc, v29, 0, s[26:27]
	v_cmp_ge_u32_e64 s[26:27], v242, v27
	v_addc_co_u32_e64 v28, vcc, v28, 0, s[22:23]
	v_cmp_ge_u32_e64 s[22:23], v243, v27
	v_addc_co_u32_e64 v29, vcc, v29, 0, s[24:25]
	v_cmp_ge_u32_e64 s[24:25], v244, v27
	v_addc_co_u32_e64 v28, vcc, v28, 0, s[26:27]
	v_cmp_ge_u32_e64 s[26:27], v245, v27
	v_addc_co_u32_e64 v29, vcc, v29, 0, s[22:23]
	v_cmp_ge_u32_e64 s[22:23], v246, v27
	v_addc_co_u32_e64 v28, vcc, v28, 0, s[24:25]
	v_cmp_ge_u32_e64 s[24:25], v247, v27
	v_addc_co_u32_e64 v29, vcc, v29, 0, s[26:27]
	v_cmp_ge_u32_e64 s[26:27], v248, v27
	v_addc_co_u32_e64 v28, vcc, v28, 0, s[22:23]
	v_cmp_ge_u32_e64 s[22:23], v249, v27
	v_addc_co_u32_e64 v29, vcc, v29, 0, s[24:25]
	v_cmp_ge_u32_e64 s[24:25], v252, v27
	v_addc_co_u32_e64 v28, vcc, v28, 0, s[26:27]
	v_cmp_ge_u32_e64 s[26:27], v253, v27
	v_addc_co_u32_e64 v29, vcc, v29, 0, s[22:23]
	v_cmp_ge_u32_e64 s[22:23], v254, v27
	v_addc_co_u32_e64 v28, vcc, v28, 0, s[24:25]
	v_cmp_ge_u32_e64 s[24:25], v255, v27
	v_addc_co_u32_e64 v29, vcc, v29, 0, s[26:27]
	v_cmp_ge_u32_e64 s[26:27], v6, v27
	v_addc_co_u32_e64 v28, vcc, v28, 0, s[22:23]
	v_cmp_ge_u32_e64 s[22:23], v7, v27
	v_addc_co_u32_e64 v29, vcc, v29, 0, s[24:25]
	v_cmp_ge_u32_e64 s[24:25], v8, v27
	v_addc_co_u32_e64 v28, vcc, v28, 0, s[26:27]
	v_cmp_ge_u32_e64 s[26:27], v9, v27
	v_addc_co_u32_e64 v29, vcc, v29, 0, s[22:23]
	v_cmp_ge_u32_e64 s[22:23], v10, v27
	v_addc_co_u32_e64 v28, vcc, v28, 0, s[24:25]
	v_cmp_ge_u32_e64 s[24:25], v11, v27
	v_addc_co_u32_e64 v29, vcc, v29, 0, s[26:27]
	v_addc_co_u32_e64 v28, vcc, v28, 0, s[22:23]
	v_addc_co_u32_e64 v29, vcc, v29, 0, s[24:25]
	v_add_u32_e32 v30, v28, v29
	s_nop 1
	v_add_u32_dpp v24, v30, v30 quad_perm:[1,0,3,2] row_mask:0xf bank_mask:0xf
	s_nop 1
	v_add_u32_dpp v25, v24, v24 quad_perm:[2,3,0,1] row_mask:0xf bank_mask:0xf
	s_nop 1
	v_add_u32_dpp v30, v25, v25 row_half_mirror row_mask:0xf bank_mask:0xf
	v_add_u32_e32 v31, -1, v27
	v_cmp_lt_u32_e64 s[24:25], s33, v30
	v_cmp_eq_u32_e64 s[26:27], s33, v30
	s_andn2_b64 s[24:25], s[24:25], s[52:53]
	s_andn2_b64 s[26:27], s[26:27], s[52:53]
	s_or_b64 s[52:53], s[52:53], s[26:27]
	v_cndmask_b32_e64 v26, v26, v27, s[24:25]
	v_cndmask_b32_e64 v26, v26, v31, s[26:27]
	s_add_i32 s98, s98, -1
	s_cmp_lt_i32 s98, 0
	s_cbranch_scc1 .Lsel_bisected
	s_cmp_eq_u64 s[52:53], -1
	s_cbranch_scc0 .Lsel_loop
; DI void cmpwin_unit(const Params& P, lptr L, int u, int tid, int lane, int wid) {
;     ...
;                     if (cnt > K) tau = trial;
;                 }
;                 int cgt = 0;
; #pragma unroll
;                 for (int ii = 0; ii < 4; ++ii) cgt += __popcll(__ballot(cand[ii] && key[ii] > tau));
;                 int need = K - cgt;
.Lsel_bisected:
	v_mov_b32_e32 v32, 0
	v_mov_b32_e32 v33, 0
	v_cmp_gt_u32_e64 s[22:23], v11, v26
	v_cmp_gt_u32_e64 s[24:25], v10, v26
	v_cmp_gt_u32_e64 s[26:27], v9, v26
	v_addc_co_u32_e64 v32, vcc, v32, v32, s[22:23]
	v_cmp_gt_u32_e64 s[22:23], v8, v26
	v_addc_co_u32_e64 v32, vcc, v32, v32, s[24:25]
	v_cmp_gt_u32_e64 s[24:25], v7, v26
	v_addc_co_u32_e64 v32, vcc, v32, v32, s[26:27]
	v_cmp_gt_u32_e64 s[26:27], v6, v26
	v_addc_co_u32_e64 v32, vcc, v32, v32, s[22:23]
	v_cmp_gt_u32_e64 s[22:23], v255, v26
	v_addc_co_u32_e64 v32, vcc, v32, v32, s[24:25]
	v_cmp_gt_u32_e64 s[24:25], v254, v26
	v_addc_co_u32_e64 v32, vcc, v32, v32, s[26:27]
	v_cmp_gt_u32_e64 s[26:27], v253, v26
	v_addc_co_u32_e64 v32, vcc, v32, v32, s[22:23]
	v_cmp_gt_u32_e64 s[22:23], v252, v26
	v_addc_co_u32_e64 v32, vcc, v32, v32, s[24:25]
	v_cmp_gt_u32_e64 s[24:25], v249, v26
	v_addc_co_u32_e64 v32, vcc, v32, v32, s[26:27]
	v_cmp_gt_u32_e64 s[26:27], v248, v26
	v_addc_co_u32_e64 v32, vcc, v32, v32, s[22:23]
	v_cmp_gt_u32_e64 s[22:23], v247, v26
	v_addc_co_u32_e64 v32, vcc, v32, v32, s[24:25]
	v_cmp_gt_u32_e64 s[24:25], v246, v26
	v_addc_co_u32_e64 v32, vcc, v32, v32, s[26:27]
	v_cmp_gt_u32_e64 s[26:27], v245, v26
	v_addc_co_u32_e64 v32, vcc, v32, v32, s[22:23]
	v_cmp_gt_u32_e64 s[22:23], v244, v26
	v_addc_co_u32_e64 v32, vcc, v32, v32, s[24:25]
	v_cmp_gt_u32_e64 s[24:25], v243, v26
	v_addc_co_u32_e64 v32, vcc, v32, v32, s[26:27]
	v_cmp_gt_u32_e64 s[26:27], v242, v26
	v_addc_co_u32_e64 v32, vcc, v32, v32, s[22:23]
	v_cmp_gt_u32_e64 s[22:23], v241, v26
	v_addc_co_u32_e64 v32, vcc, v32, v32, s[24:25]
	v_cmp_gt_u32_e64 s[24:25], v240, v26
	v_addc_co_u32_e64 v32, vcc, v32, v32, s[26:27]
	v_cmp_gt_u32_e64 s[26:27], v239, v26
	v_addc_co_u32_e64 v32, vcc, v32, v32, s[22:23]
	v_cmp_gt_u32_e64 s[22:23], v238, v26
	v_addc_co_u32_e64 v32, vcc, v32, v32, s[24:25]
	v_cmp_gt_u32_e64 s[24:25], v237, v26
	v_addc_co_u32_e64 v32, vcc, v32, v32, s[26:27]
	v_cmp_gt_u32_e64 s[26:27], v236, v26
	v_addc_co_u32_e64 v32, vcc, v32, v32, s[22:23]
	v_cmp_gt_u32_e64 s[22:23], v235, v26
	v_addc_co_u32_e64 v32, vcc, v32, v32, s[24:25]
	v_cmp_gt_u32_e64 s[24:25], v234, v26
	v_addc_co_u32_e64 v32, vcc, v32, v32, s[26:27]
	v_cmp_gt_u32_e64 s[26:27], v233, v26
	v_addc_co_u32_e64 v32, vcc, v32, v32, s[22:23]
	v_cmp_gt_u32_e64 s[22:23], v232, v26
	v_addc_co_u32_e64 v32, vcc, v32, v32, s[24:25]
	v_cmp_gt_u32_e64 s[24:25], v231, v26
	v_addc_co_u32_e64 v32, vcc, v32, v32, s[26:27]
	v_cmp_gt_u32_e64 s[26:27], v230, v26
	v_addc_co_u32_e64 v32, vcc, v32, v32, s[22:23]
	v_cmp_gt_u32_e64 s[22:23], v229, v26
	v_addc_co_u32_e64 v32, vcc, v32, v32, s[24:25]
	v_cmp_gt_u32_e64 s[24:25], v228, v26
	v_addc_co_u32_e64 v32, vcc, v32, v32, s[26:27]
	v_addc_co_u32_e64 v32, vcc, v32, v32, s[22:23]
	v_addc_co_u32_e64 v32, vcc, v32, v32, s[24:25]
	v_cmp_eq_u32_e64 s[22:23], v11, v26
	v_cmp_eq_u32_e64 s[24:25], v10, v26
	v_cmp_eq_u32_e64 s[26:27], v9, v26
	v_addc_co_u32_e64 v33, vcc, v33, v33, s[22:23]
	v_cmp_eq_u32_e64 s[22:23], v8, v26
	v_addc_co_u32_e64 v33, vcc, v33, v33, s[24:25]
	v_cmp_eq_u32_e64 s[24:25], v7, v26
	v_addc_co_u32_e64 v33, vcc, v33, v33, s[26:27]
	v_cmp_eq_u32_e64 s[26:27], v6, v26
	v_addc_co_u32_e64 v33, vcc, v33, v33, s[22:23]
	v_cmp_eq_u32_e64 s[22:23], v255, v26
	v_addc_co_u32_e64 v33, vcc, v33, v33, s[24:25]
	v_cmp_eq_u32_e64 s[24:25], v254, v26
	v_addc_co_u32_e64 v33, vcc, v33, v33, s[26:27]
	v_cmp_eq_u32_e64 s[26:27], v253, v26
	v_addc_co_u32_e64 v33, vcc, v33, v33, s[22:23]
	v_cmp_eq_u32_e64 s[22:23], v252, v26
	v_addc_co_u32_e64 v33, vcc, v33, v33, s[24:25]
	v_cmp_eq_u32_e64 s[24:25], v249, v26
	v_addc_co_u32_e64 v33, vcc, v33, v33, s[26:27]
	v_cmp_eq_u32_e64 s[26:27], v248, v26
	v_addc_co_u32_e64 v33, vcc, v33, v33, s[22:23]
	v_cmp_eq_u32_e64 s[22:23], v247, v26
	v_addc_co_u32_e64 v33, vcc, v33, v33, s[24:25]
	v_cmp_eq_u32_e64 s[24:25], v246, v26
	v_addc_co_u32_e64 v33, vcc, v33, v33, s[26:27]
	v_cmp_eq_u32_e64 s[26:27], v245, v26
	v_addc_co_u32_e64 v33, vcc, v33, v33, s[22:23]
	v_cmp_eq_u32_e64 s[22:23], v244, v26
	v_addc_co_u32_e64 v33, vcc, v33, v33, s[24:25]
	v_cmp_eq_u32_e64 s[24:25], v243, v26
	v_addc_co_u32_e64 v33, vcc, v33, v33, s[26:27]
	v_cmp_eq_u32_e64 s[26:27], v242, v26
	v_addc_co_u32_e64 v33, vcc, v33, v33, s[22:23]
	v_cmp_eq_u32_e64 s[22:23], v241, v26
	v_addc_co_u32_e64 v33, vcc, v33, v33, s[24:25]
	v_cmp_eq_u32_e64 s[24:25], v240, v26
	v_addc_co_u32_e64 v33, vcc, v33, v33, s[26:27]
	v_cmp_eq_u32_e64 s[26:27], v239, v26
	v_addc_co_u32_e64 v33, vcc, v33, v33, s[22:23]
	v_cmp_eq_u32_e64 s[22:23], v238, v26
	v_addc_co_u32_e64 v33, vcc, v33, v33, s[24:25]
	v_cmp_eq_u32_e64 s[24:25], v237, v26
	v_addc_co_u32_e64 v33, vcc, v33, v33, s[26:27]
	v_cmp_eq_u32_e64 s[26:27], v236, v26
	v_addc_co_u32_e64 v33, vcc, v33, v33, s[22:23]
	v_cmp_eq_u32_e64 s[22:23], v235, v26
	v_addc_co_u32_e64 v33, vcc, v33, v33, s[24:25]
	v_cmp_eq_u32_e64 s[24:25], v234, v26
	v_addc_co_u32_e64 v33, vcc, v33, v33, s[26:27]
	v_cmp_eq_u32_e64 s[26:27], v233, v26
	v_addc_co_u32_e64 v33, vcc, v33, v33, s[22:23]
	v_cmp_eq_u32_e64 s[22:23], v232, v26
	v_addc_co_u32_e64 v33, vcc, v33, v33, s[24:25]
	v_cmp_eq_u32_e64 s[24:25], v231, v26
	v_addc_co_u32_e64 v33, vcc, v33, v33, s[26:27]
	v_cmp_eq_u32_e64 s[26:27], v230, v26
	v_addc_co_u32_e64 v33, vcc, v33, v33, s[22:23]
	v_cmp_eq_u32_e64 s[22:23], v229, v26
	v_addc_co_u32_e64 v33, vcc, v33, v33, s[24:25]
	v_cmp_eq_u32_e64 s[24:25], v228, v26
	v_addc_co_u32_e64 v33, vcc, v33, v33, s[26:27]
	v_addc_co_u32_e64 v33, vcc, v33, v33, s[22:23]
	v_addc_co_u32_e64 v33, vcc, v33, v33, s[24:25]
	v_and_b32_e32 v33, v33, v22
	v_bcnt_u32_b32 v30, v32, 0
	s_nop 1
	v_add_u32_dpp v24, v30, v30 quad_perm:[1,0,3,2] row_mask:0xf bank_mask:0xf
	s_nop 1
	v_add_u32_dpp v25, v24, v24 quad_perm:[2,3,0,1] row_mask:0xf bank_mask:0xf
	s_nop 1
	v_add_u32_dpp v30, v25, v25 row_half_mirror row_mask:0xf bank_mask:0xf
	v_sub_u32_e32 v16, s33, v30
	v_cmp_lt_i32_e32 vcc, 0, v16
	s_cbranch_vccz .Lsel_merge
; #define LAS __attribute__((address_space(3)))
; DI void cmpwin_unit(const Params& P, lptr L, int u, int tid, int lane, int wid) {
;     ...
;                 int need = K - cgt;
; #pragma unroll
;                 for (int ii = 0; ii < 4; ++ii) {
;                     const bool eq = cand[ii] && key[ii] == tau;
;                     const unsigned long long bal = __ballot(eq);
;                     const int rank = __popcll(bal & lt_mask);
;                     selb[ii] = selb[ii] || (cand[ii] && key[ii] > tau) || (eq && rank < need);
;                     need = max(0, need - (int)__popcll(bal));
;                 }
;             }
;             LAS unsigned* mrow = (LAS unsigned*)(L + AL_SM) + q * 8; (void)tq;
; #pragma unroll
;             for (int ii = 0; ii < 4; ++ii) { const unsigned long long bal = __ballot(selb[ii]); if (lane == 0) { mrow[2 * ii] = (unsigned)bal; mrow[2 * ii + 1] = (unsigned)(bal >> 32); } }
	v_bcnt_u32_b32 v0, v33, 0
	v_cmp_le_u32_e64 s[22:23], 1, v12
	v_cmp_le_u32_e64 s[24:25], 2, v12
	v_cmp_le_u32_e64 s[26:27], 4, v12
	v_mov_b32_e32 v24, 0
	s_nop 0
	v_mov_b32_dpp v24, v0 row_shr:1 row_mask:0xf bank_mask:0xf bound_ctrl:0
	s_nop 1
	v_cndmask_b32_e64 v24, 0, v24, s[22:23]
	v_add_u32_e32 v7, v0, v24
	v_mov_b32_e32 v24, 0
	s_nop 0
	v_mov_b32_dpp v24, v7 row_shr:2 row_mask:0xf bank_mask:0xf bound_ctrl:0
	s_nop 1
	v_cndmask_b32_e64 v24, 0, v24, s[24:25]
	v_add_u32_e32 v7, v7, v24
	v_mov_b32_e32 v24, 0
	s_nop 0
	v_mov_b32_dpp v24, v7 row_shr:4 row_mask:0xf bank_mask:0xf bound_ctrl:0
	s_nop 1
	v_cndmask_b32_e64 v24, 0, v24, s[26:27]
	v_add_u32_e32 v7, v7, v24
	v_sub_u32_e32 v7, v7, v0
	v_sub_u32_e32 v7, v16, v7
	v_max_i32_e32 v7, 0, v7
	v_min_i32_e32 v7, v7, v0
	v_mov_b32_e32 v25, v33
	v_cmp_lt_u32_e32 vcc, 0, v7
	v_add_u32_e32 v24, -1, v25
	v_and_b32_e32 v24, v25, v24
	v_cndmask_b32_e32 v25, v25, v24, vcc
	v_cmp_lt_u32_e32 vcc, 1, v7
	v_add_u32_e32 v24, -1, v25
	v_and_b32_e32 v24, v25, v24
	v_cndmask_b32_e32 v25, v25, v24, vcc
	v_cmp_lt_u32_e32 vcc, 2, v7
	v_add_u32_e32 v24, -1, v25
	v_and_b32_e32 v24, v25, v24
	v_cndmask_b32_e32 v25, v25, v24, vcc
	v_cmp_lt_u32_e32 vcc, 3, v7
	v_add_u32_e32 v24, -1, v25
	v_and_b32_e32 v24, v25, v24
	v_cndmask_b32_e32 v25, v25, v24, vcc
	v_cmp_lt_u32_e32 vcc, 4, v7
	v_add_u32_e32 v24, -1, v25
	v_and_b32_e32 v24, v25, v24
	v_cndmask_b32_e32 v25, v25, v24, vcc
	v_cmp_lt_u32_e32 vcc, 5, v7
	v_add_u32_e32 v24, -1, v25
	v_and_b32_e32 v24, v25, v24
	v_cndmask_b32_e32 v25, v25, v24, vcc
	v_cmp_lt_u32_e32 vcc, 6, v7
	v_add_u32_e32 v24, -1, v25
	v_and_b32_e32 v24, v25, v24
	v_cndmask_b32_e32 v25, v25, v24, vcc
	v_cmp_lt_u32_e32 vcc, 7, v7
	v_add_u32_e32 v24, -1, v25
	v_and_b32_e32 v24, v25, v24
	v_cndmask_b32_e32 v25, v25, v24, vcc
	v_cmp_lt_u32_e32 vcc, 8, v7
	v_add_u32_e32 v24, -1, v25
	v_and_b32_e32 v24, v25, v24
	v_cndmask_b32_e32 v25, v25, v24, vcc
	v_cmp_lt_u32_e32 vcc, 9, v7
	v_add_u32_e32 v24, -1, v25
	v_and_b32_e32 v24, v25, v24
	v_cndmask_b32_e32 v25, v25, v24, vcc
	v_cmp_lt_u32_e32 vcc, 10, v7
	v_add_u32_e32 v24, -1, v25
	v_and_b32_e32 v24, v25, v24
	v_cndmask_b32_e32 v25, v25, v24, vcc
	v_cmp_lt_u32_e32 vcc, 11, v7
	v_add_u32_e32 v24, -1, v25
	v_and_b32_e32 v24, v25, v24
	v_cndmask_b32_e32 v25, v25, v24, vcc
	v_cmp_lt_u32_e32 vcc, 12, v7
	v_add_u32_e32 v24, -1, v25
	v_and_b32_e32 v24, v25, v24
	v_cndmask_b32_e32 v25, v25, v24, vcc
	v_xor_b32_e32 v25, v33, v25
	v_or_b32_e32 v32, v32, v25
.Lsel_merge:
	v_or_b32_e32 v32, v32, v23
.Lsel_store:
	s_waitcnt lgkmcnt(0)
	v_lshl_add_u32 v24, v192, 2, s101
	ds_write_b32 v24, v32

; __global__ void __launch_bounds__(512) fwd_kernel(Params P) {
;     extern __shared__ __attribute__((aligned(16))) unsigned char lds_raw[];
	.amdhsa_kernel _Z10fwd_kernel6Params
		.amdhsa_group_segment_fixed_size 0
		.amdhsa_private_segment_fixed_size 0
		.amdhsa_kernarg_size 392
		.amdhsa_user_sgpr_count 2
		.amdhsa_user_sgpr_dispatch_ptr 0
		.amdhsa_user_sgpr_queue_ptr 0
		.amdhsa_user_sgpr_kernarg_segment_ptr 1
		.amdhsa_user_sgpr_dispatch_id 0
		.amdhsa_user_sgpr_kernarg_preload_length 0
		.amdhsa_user_sgpr_kernarg_preload_offset 0
		.amdhsa_user_sgpr_private_segment_size 0
		.amdhsa_uses_dynamic_stack 0
		.amdhsa_enable_private_segment 0
		.amdhsa_system_sgpr_workgroup_id_x 1
		.amdhsa_system_sgpr_workgroup_id_y 0
		.amdhsa_system_sgpr_workgroup_id_z 0
		.amdhsa_system_sgpr_workgroup_info 0
		.amdhsa_system_vgpr_workitem_id 2
		.amdhsa_next_free_vgpr 256
		.amdhsa_next_free_sgpr 102
		.amdhsa_accum_offset 256
		.amdhsa_reserve_vcc 1
		.amdhsa_float_round_mode_32 0
		.amdhsa_float_round_mode_16_64 0
		.amdhsa_float_denorm_mode_32 3
		.amdhsa_float_denorm_mode_16_64 3
		.amdhsa_dx10_clamp 1
		.amdhsa_ieee_mode 1
		.amdhsa_fp16_overflow 0
		.amdhsa_tg_split 0
		.amdhsa_exception_fp_ieee_invalid_op 0
		.amdhsa_exception_fp_denorm_src 0
		.amdhsa_exception_fp_ieee_div_zero 0
		.amdhsa_exception_fp_ieee_overflow 0
		.amdhsa_exception_fp_ieee_underflow 0
		.amdhsa_exception_fp_ieee_inexact 0
		.amdhsa_exception_int_div_zero 0
	.end_amdhsa_kernel

; __global__ void __launch_bounds__(512) fwd_kernel(Params P) {
;     extern __shared__ __attribute__((aligned(16))) unsigned char lds_raw[];
amdhsa.kernels:
  - .agpr_count:     0
    .args:
      - .offset:         0
        .size:           136
        .value_kind:     by_value
      - .offset:         136
        .size:           4
        .value_kind:     hidden_block_count_x
      - .offset:         140
        .size:           4
        .value_kind:     hidden_block_count_y
      - .offset:         144
        .size:           4
        .value_kind:     hidden_block_count_z
      - .offset:         148
        .size:           2
        .value_kind:     hidden_group_size_x
      - .offset:         150
        .size:           2
        .value_kind:     hidden_group_size_y
      - .offset:         152
        .size:           2
        .value_kind:     hidden_group_size_z
      - .offset:         154
        .size:           2
        .value_kind:     hidden_remainder_x
      - .offset:         156
        .size:           2
        .value_kind:     hidden_remainder_y
      - .offset:         158
        .size:           2
        .value_kind:     hidden_remainder_z
      - .offset:         176
        .size:           8
        .value_kind:     hidden_global_offset_x
      - .offset:         184
        .size:           8
        .value_kind:     hidden_global_offset_y
      - .offset:         192
        .size:           8
        .value_kind:     hidden_global_offset_z
      - .offset:         200
        .size:           2
        .value_kind:     hidden_grid_dims
      - .offset:         224
        .size:           8
        .value_kind:     hidden_multigrid_sync_arg
      - .offset:         256
        .size:           4
        .value_kind:     hidden_dynamic_lds_size
    .group_segment_fixed_size: 0
    .kernarg_segment_align: 8
    .kernarg_segment_size: 392
    .language:       OpenCL C
    .language_version:
      - 2
      - 0
    .max_flat_workgroup_size: 512
    .name:           _Z10fwd_kernel6Params
    .private_segment_fixed_size: 0
    .sgpr_count:     108
    .sgpr_spill_count: 101
    .symbol:         _Z10fwd_kernel6Params.kd
    .uniform_work_group_size: 1
    .uses_dynamic_stack: false
    .vgpr_count:     256
    .vgpr_spill_count: 0
    .wavefront_size: 64
